# v81 + residual epilogue (FFN1 down, out-proj): second-half xin loads issued into dead first-half registers before the first-half stores, pk ops hoisted; same arithmetic
# baseline (speedup 1.0000x reference)
.LBB0_367:
	v_lshl_add_u32 v202, s25, 8, v212
	v_lshl_or_b32 v200, s24, 8, v214
	v_ashrrev_i32_e32 v201, 31, v200
	v_ashrrev_i32_e32 v203, 31, v202
	v_lshl_add_u64 v[204:205], v[200:201], 2, s[12:13]
	v_lshlrev_b64 v[130:131], 12, v[202:203]
	v_or_b32_e32 v210, 16, v202
	v_lshl_add_u64 v[130:131], v[204:205], 0, v[130:131]
	v_ashrrev_i32_e32 v211, 31, v210
	global_load_dwordx4 v[218:221], v[130:131], off offset:16
	global_load_dwordx4 v[248:251], v[130:131], off
	global_load_dwordx4 v[234:237], v[130:131], off offset:528
	global_load_dwordx4 v[238:241], v[130:131], off offset:512
	v_lshlrev_b64 v[130:131], 12, v[210:211]
	v_or_b32_e32 v208, 32, v202
	v_lshl_add_u64 v[130:131], v[204:205], 0, v[130:131]
	v_ashrrev_i32_e32 v209, 31, v208
	global_load_dwordx4 v[170:173], v[130:131], off offset:16
	global_load_dwordx4 v[174:177], v[130:131], off
	global_load_dwordx4 v[162:165], v[130:131], off offset:528
	global_load_dwordx4 v[166:169], v[130:131], off offset:512
	v_lshlrev_b64 v[130:131], 12, v[208:209]
	v_or_b32_e32 v206, 48, v202
	v_lshl_add_u64 v[130:131], v[204:205], 0, v[130:131]
	v_ashrrev_i32_e32 v207, 31, v206
	global_load_dwordx4 v[154:157], v[130:131], off offset:16
	global_load_dwordx4 v[158:161], v[130:131], off
	global_load_dwordx4 v[146:149], v[130:131], off offset:528
	global_load_dwordx4 v[150:153], v[130:131], off offset:512
	v_lshlrev_b64 v[130:131], 12, v[206:207]
	v_lshl_add_u64 v[134:135], v[204:205], 0, v[130:131]
	global_load_dwordx4 v[138:141], v[134:135], off offset:16
	global_load_dwordx4 v[142:145], v[134:135], off
	global_load_dwordx4 v[130:133], v[134:135], off offset:528
	s_nop 0
	global_load_dwordx4 v[134:137], v[134:135], off offset:512
	v_and_b32_e32 v195, 64, v245
	v_xor_b32_e32 v194, 16, v245
	v_add_u32_e32 v195, 64, v195
	v_cmp_lt_i32_e32 vcc, v194, v195
	s_lshl_b32 s36, s24, 2
	s_ashr_i32 s37, s36, 31
	v_cndmask_b32_e32 v194, v245, v194, vcc
	v_lshlrev_b32_e32 v217, 2, v194
	v_xor_b32_e32 v194, 32, v245
	v_cmp_lt_i32_e32 vcc, v194, v195
	s_nop 1
	v_cndmask_b32_e32 v194, v245, v194, vcc
	v_lshlrev_b32_e32 v216, 2, v194
	v_lshlrev_b64 v[194:195], 10, v[202:203]
	v_lshl_add_u64 v[194:195], v[194:195], 0, v[200:201]
	s_waitcnt vmcnt(0)
	v_pk_fma_f32 v[128:129], v[128:129], 0.5, v[250:251] op_sel_hi:[1,0,1]
	v_pk_fma_f32 v[126:127], v[126:127], 0.5, v[248:249] op_sel_hi:[1,0,1]
	v_pk_fma_f32 v[124:125], v[124:125], 0.5, v[220:221] op_sel_hi:[1,0,1]
	v_pk_fma_f32 v[122:123], v[122:123], 0.5, v[218:219] op_sel_hi:[1,0,1]
	v_pk_fma_f32 v[120:121], v[120:121], 0.5, v[240:241] op_sel_hi:[1,0,1]
	v_pk_fma_f32 v[118:119], v[118:119], 0.5, v[238:239] op_sel_hi:[1,0,1]
	v_pk_fma_f32 v[114:115], v[114:115], 0.5, v[234:235] op_sel_hi:[1,0,1]
	v_pk_fma_f32 v[116:117], v[116:117], 0.5, v[236:237] op_sel_hi:[1,0,1]
	v_pk_fma_f32 v[110:111], v[110:111], 0.5, v[176:177] op_sel_hi:[1,0,1]
	v_pk_fma_f32 v[108:109], v[108:109], 0.5, v[174:175] op_sel_hi:[1,0,1]
	v_pk_fma_f32 v[106:107], v[106:107], 0.5, v[172:173] op_sel_hi:[1,0,1]
	v_pk_fma_f32 v[104:105], v[104:105], 0.5, v[170:171] op_sel_hi:[1,0,1]
	v_pk_fma_f32 v[102:103], v[102:103], 0.5, v[168:169] op_sel_hi:[1,0,1]
	v_pk_fma_f32 v[100:101], v[100:101], 0.5, v[166:167] op_sel_hi:[1,0,1]
	v_pk_fma_f32 v[96:97], v[96:97], 0.5, v[162:163] op_sel_hi:[1,0,1]
	v_pk_fma_f32 v[98:99], v[98:99], 0.5, v[164:165] op_sel_hi:[1,0,1]
	v_pk_fma_f32 v[94:95], v[94:95], 0.5, v[160:161] op_sel_hi:[1,0,1]
	v_pk_fma_f32 v[92:93], v[92:93], 0.5, v[158:159] op_sel_hi:[1,0,1]
	v_pk_fma_f32 v[90:91], v[90:91], 0.5, v[156:157] op_sel_hi:[1,0,1]
	v_pk_fma_f32 v[88:89], v[88:89], 0.5, v[154:155] op_sel_hi:[1,0,1]
	v_pk_fma_f32 v[86:87], v[86:87], 0.5, v[152:153] op_sel_hi:[1,0,1]
	v_pk_fma_f32 v[84:85], v[84:85], 0.5, v[150:151] op_sel_hi:[1,0,1]
	v_pk_fma_f32 v[80:81], v[80:81], 0.5, v[146:147] op_sel_hi:[1,0,1]
	v_pk_fma_f32 v[82:83], v[82:83], 0.5, v[148:149] op_sel_hi:[1,0,1]
	v_pk_fma_f32 v[78:79], v[78:79], 0.5, v[144:145] op_sel_hi:[1,0,1]
	v_pk_fma_f32 v[76:77], v[76:77], 0.5, v[142:143] op_sel_hi:[1,0,1]
	v_pk_fma_f32 v[74:75], v[74:75], 0.5, v[140:141] op_sel_hi:[1,0,1]
	v_pk_fma_f32 v[72:73], v[72:73], 0.5, v[138:139] op_sel_hi:[1,0,1]
	v_pk_fma_f32 v[70:71], v[70:71], 0.5, v[136:137] op_sel_hi:[1,0,1]
	v_pk_fma_f32 v[68:69], v[68:69], 0.5, v[134:135] op_sel_hi:[1,0,1]
	v_pk_fma_f32 v[64:65], v[64:65], 0.5, v[130:131] op_sel_hi:[1,0,1]
	v_pk_fma_f32 v[66:67], v[66:67], 0.5, v[132:133] op_sel_hi:[1,0,1]
	v_lshl_add_u64 v[196:197], v[194:195], 2, s[14:15]
	global_store_dwordx4 v[196:197], v[126:129], off
	global_store_dwordx4 v[196:197], v[122:125], off offset:16
	v_cvt_pk_bf16_f32 v218, v126, v127
	v_mul_f32_e32 v127, v127, v127
	v_fmac_f32_e32 v127, v126, v126
	v_mul_f32_e32 v126, v129, v129
	v_cvt_pk_bf16_f32 v220, v122, v123
	v_fmac_f32_e32 v126, v128, v128
	v_mul_f32_e32 v123, v123, v123
	v_add_f32_e32 v126, v127, v126
	v_fmac_f32_e32 v123, v122, v122
	v_add_f32_e32 v122, v123, v126
	v_mul_f32_e32 v123, v125, v125
	v_fmac_f32_e32 v123, v124, v124
	v_cvt_pk_bf16_f32 v221, v124, v125
	v_add_f32_e32 v122, v123, v122
	v_mul_f32_e32 v123, v119, v119
	v_mul_f32_e32 v124, v121, v121
	v_fmac_f32_e32 v123, v118, v118
	v_fmac_f32_e32 v124, v120, v120
	v_add_f32_e32 v123, v123, v124
	v_mul_f32_e32 v124, v115, v115
	v_fmac_f32_e32 v124, v114, v114
	v_add_f32_e32 v123, v124, v123
	v_mul_f32_e32 v124, v117, v117
	v_fmac_f32_e32 v124, v116, v116
	v_add_f32_e32 v123, v124, v123
	v_add_f32_e32 v122, v122, v123
	ds_bpermute_b32 v123, v217, v122
	v_lshlrev_b64 v[194:195], 1, v[194:195]
	v_cvt_pk_bf16_f32 v219, v128, v129
	v_lshl_add_u64 v[222:223], s[20:21], 0, v[194:195]
	global_store_dwordx4 v[222:223], v[218:221], off
	v_add_u32_e32 v238, 0x80, v202
	v_ashrrev_i32_e32 v239, 31, v238
	v_lshlrev_b64 v[238:239], 12, v[238:239]
	v_lshl_add_u64 v[238:239], v[204:205], 0, v[238:239]
	global_load_dwordx4 v[218:221], v[238:239], off offset:16
	global_load_dwordx4 v[248:251], v[238:239], off
	global_load_dwordx4 v[234:237], v[238:239], off offset:528
	s_nop 0
	global_load_dwordx4 v[238:241], v[238:239], off offset:512
	v_add_u32_e32 v166, 0x80, v210
	v_ashrrev_i32_e32 v167, 31, v166
	v_lshlrev_b64 v[166:167], 12, v[166:167]
	v_lshl_add_u64 v[166:167], v[204:205], 0, v[166:167]
	global_load_dwordx4 v[170:173], v[166:167], off offset:16
	global_load_dwordx4 v[174:177], v[166:167], off
	global_load_dwordx4 v[162:165], v[166:167], off offset:528
	s_nop 0
	global_load_dwordx4 v[166:169], v[166:167], off offset:512
	v_add_u32_e32 v150, 0x80, v208
	v_ashrrev_i32_e32 v151, 31, v150
	v_lshlrev_b64 v[150:151], 12, v[150:151]
	v_lshl_add_u64 v[150:151], v[204:205], 0, v[150:151]
	global_load_dwordx4 v[154:157], v[150:151], off offset:16
	global_load_dwordx4 v[158:161], v[150:151], off
	global_load_dwordx4 v[146:149], v[150:151], off offset:528
	s_nop 0
	global_load_dwordx4 v[150:153], v[150:151], off offset:512
	v_add_u32_e32 v134, 0x80, v206
	v_ashrrev_i32_e32 v135, 31, v134
	v_lshlrev_b64 v[134:135], 12, v[134:135]
	v_lshl_add_u64 v[134:135], v[204:205], 0, v[134:135]
	global_load_dwordx4 v[138:141], v[134:135], off offset:16
	global_load_dwordx4 v[142:145], v[134:135], off
	global_load_dwordx4 v[130:133], v[134:135], off offset:528
	s_nop 0
	global_load_dwordx4 v[134:137], v[134:135], off offset:512
	global_store_dwordx4 v[196:197], v[118:121], off offset:512
	global_store_dwordx4 v[196:197], v[114:117], off offset:528
	v_or_b32_e32 v194, 0x100, v194
	v_cvt_pk_bf16_f32 v118, v118, v119
	v_cvt_pk_bf16_f32 v119, v120, v121
	v_cvt_pk_bf16_f32 v120, v114, v115
	s_waitcnt lgkmcnt(0)
	v_add_f32_e32 v114, v122, v123
	ds_bpermute_b32 v115, v216, v114
	v_cvt_pk_bf16_f32 v121, v116, v117
	v_lshl_add_u64 v[116:117], s[20:21], 0, v[194:195]
	global_store_dwordx4 v[116:117], v[118:121], off
	s_and_saveexec_b64 s[24:25], s[4:5]
	s_cbranch_execz .LBB0_369
	v_lshlrev_b64 v[116:117], 6, v[202:203]
	v_lshl_add_u64 v[116:117], s[22:23], 0, v[116:117]
	v_lshl_add_u64 v[116:117], s[36:37], 2, v[116:117]
	s_lshl_b32 s90, s59, 2
	v_lshl_add_u64 v[116:117], v[116:117], 0, s[90:91]
	s_waitcnt lgkmcnt(0)
	v_add_f32_e32 v114, v114, v115
	global_store_dword v[116:117], v114, off
.LBB0_369:
	s_or_b64 exec, exec, s[24:25]
	s_waitcnt lgkmcnt(0)
	v_lshlrev_b64 v[114:115], 10, v[210:211]
	v_lshl_add_u64 v[118:119], v[114:115], 0, v[200:201]
	v_lshl_add_u64 v[120:121], v[118:119], 2, s[14:15]
	global_store_dwordx4 v[120:121], v[108:111], off
	global_store_dwordx4 v[120:121], v[104:107], off offset:16
	v_cvt_pk_bf16_f32 v114, v108, v109
	v_mul_f32_e32 v109, v109, v109
	v_fmac_f32_e32 v109, v108, v108
	v_mul_f32_e32 v108, v111, v111
	v_cvt_pk_bf16_f32 v116, v104, v105
	v_fmac_f32_e32 v108, v110, v110
	v_mul_f32_e32 v105, v105, v105
	v_add_f32_e32 v108, v109, v108
	v_fmac_f32_e32 v105, v104, v104
	v_add_f32_e32 v104, v105, v108
	v_mul_f32_e32 v105, v107, v107
	v_fmac_f32_e32 v105, v106, v106
	v_cvt_pk_bf16_f32 v117, v106, v107
	v_add_f32_e32 v104, v105, v104
	v_mul_f32_e32 v105, v101, v101
	v_mul_f32_e32 v106, v103, v103
	v_fmac_f32_e32 v105, v100, v100
	v_fmac_f32_e32 v106, v102, v102
	v_add_f32_e32 v105, v105, v106
	v_mul_f32_e32 v106, v97, v97
	v_fmac_f32_e32 v106, v96, v96
	v_add_f32_e32 v105, v106, v105
	v_mul_f32_e32 v106, v99, v99
	v_fmac_f32_e32 v106, v98, v98
	v_add_f32_e32 v105, v106, v105
	v_add_f32_e32 v104, v104, v105
	ds_bpermute_b32 v105, v217, v104
	v_lshlrev_b64 v[118:119], 1, v[118:119]
	v_cvt_pk_bf16_f32 v115, v110, v111
	v_lshl_add_u64 v[122:123], s[20:21], 0, v[118:119]
	global_store_dwordx4 v[122:123], v[114:117], off
	global_store_dwordx4 v[120:121], v[100:103], off offset:512
	global_store_dwordx4 v[120:121], v[96:99], off offset:528
	v_or_b32_e32 v118, 0x100, v118
	v_cvt_pk_bf16_f32 v100, v100, v101
	v_cvt_pk_bf16_f32 v101, v102, v103
	v_cvt_pk_bf16_f32 v102, v96, v97
	s_waitcnt lgkmcnt(0)
	v_add_f32_e32 v96, v104, v105
	ds_bpermute_b32 v97, v216, v96
	v_cvt_pk_bf16_f32 v103, v98, v99
	v_lshl_add_u64 v[98:99], s[20:21], 0, v[118:119]
	global_store_dwordx4 v[98:99], v[100:103], off
	s_and_saveexec_b64 s[24:25], s[4:5]
	s_cbranch_execz .LBB0_371
	v_lshlrev_b64 v[98:99], 6, v[210:211]
	v_lshl_add_u64 v[98:99], s[22:23], 0, v[98:99]
	v_lshl_add_u64 v[98:99], s[36:37], 2, v[98:99]
	s_lshl_b32 s90, s59, 2
	v_lshl_add_u64 v[98:99], v[98:99], 0, s[90:91]
	s_waitcnt lgkmcnt(0)
	v_add_f32_e32 v96, v96, v97
	global_store_dword v[98:99], v96, off
.LBB0_371:
	s_or_b64 exec, exec, s[24:25]
	s_waitcnt lgkmcnt(0)
	v_lshlrev_b64 v[96:97], 10, v[208:209]
	v_lshl_add_u64 v[100:101], v[96:97], 0, v[200:201]
	v_lshl_add_u64 v[102:103], v[100:101], 2, s[14:15]
	global_store_dwordx4 v[102:103], v[92:95], off
	global_store_dwordx4 v[102:103], v[88:91], off offset:16
	v_cvt_pk_bf16_f32 v96, v92, v93
	v_mul_f32_e32 v93, v93, v93
	v_fmac_f32_e32 v93, v92, v92
	v_mul_f32_e32 v92, v95, v95
	v_cvt_pk_bf16_f32 v98, v88, v89
	v_fmac_f32_e32 v92, v94, v94
	v_mul_f32_e32 v89, v89, v89
	v_add_f32_e32 v92, v93, v92
	v_fmac_f32_e32 v89, v88, v88
	v_add_f32_e32 v88, v89, v92
	v_mul_f32_e32 v89, v91, v91
	v_fmac_f32_e32 v89, v90, v90
	v_cvt_pk_bf16_f32 v99, v90, v91
	v_add_f32_e32 v88, v89, v88
	v_mul_f32_e32 v89, v85, v85
	v_mul_f32_e32 v90, v87, v87
	v_fmac_f32_e32 v89, v84, v84
	v_fmac_f32_e32 v90, v86, v86
	v_add_f32_e32 v89, v89, v90
	v_mul_f32_e32 v90, v81, v81
	v_fmac_f32_e32 v90, v80, v80
	v_add_f32_e32 v89, v90, v89
	v_mul_f32_e32 v90, v83, v83
	v_fmac_f32_e32 v90, v82, v82
	v_add_f32_e32 v89, v90, v89
	v_add_f32_e32 v88, v88, v89
	ds_bpermute_b32 v89, v217, v88
	v_lshlrev_b64 v[100:101], 1, v[100:101]
	v_cvt_pk_bf16_f32 v97, v94, v95
	v_lshl_add_u64 v[104:105], s[20:21], 0, v[100:101]
	global_store_dwordx4 v[104:105], v[96:99], off
	global_store_dwordx4 v[102:103], v[84:87], off offset:512
	global_store_dwordx4 v[102:103], v[80:83], off offset:528
	v_or_b32_e32 v100, 0x100, v100
	v_cvt_pk_bf16_f32 v84, v84, v85
	v_cvt_pk_bf16_f32 v85, v86, v87
	v_cvt_pk_bf16_f32 v86, v80, v81
	s_waitcnt lgkmcnt(0)
	v_add_f32_e32 v80, v88, v89
	ds_bpermute_b32 v81, v216, v80
	v_cvt_pk_bf16_f32 v87, v82, v83
	v_lshl_add_u64 v[82:83], s[20:21], 0, v[100:101]
	global_store_dwordx4 v[82:83], v[84:87], off
	s_and_saveexec_b64 s[24:25], s[4:5]
	s_cbranch_execz .LBB0_373
	v_lshlrev_b64 v[82:83], 6, v[208:209]
	v_lshl_add_u64 v[82:83], s[22:23], 0, v[82:83]
	v_lshl_add_u64 v[82:83], s[36:37], 2, v[82:83]
	s_lshl_b32 s90, s59, 2
	v_lshl_add_u64 v[82:83], v[82:83], 0, s[90:91]
	s_waitcnt lgkmcnt(0)
	v_add_f32_e32 v80, v80, v81
	global_store_dword v[82:83], v80, off
.LBB0_373:
	s_or_b64 exec, exec, s[24:25]
	s_waitcnt lgkmcnt(0)
	v_lshlrev_b64 v[80:81], 10, v[206:207]
	v_lshl_add_u64 v[84:85], v[80:81], 0, v[200:201]
	v_lshl_add_u64 v[86:87], v[84:85], 2, s[14:15]
	global_store_dwordx4 v[86:87], v[76:79], off
	global_store_dwordx4 v[86:87], v[72:75], off offset:16
	v_cvt_pk_bf16_f32 v80, v76, v77
	v_mul_f32_e32 v77, v77, v77
	v_fmac_f32_e32 v77, v76, v76
	v_mul_f32_e32 v76, v79, v79
	v_cvt_pk_bf16_f32 v82, v72, v73
	v_fmac_f32_e32 v76, v78, v78
	v_mul_f32_e32 v73, v73, v73
	v_add_f32_e32 v76, v77, v76
	v_fmac_f32_e32 v73, v72, v72
	v_add_f32_e32 v72, v73, v76
	v_mul_f32_e32 v73, v75, v75
	v_fmac_f32_e32 v73, v74, v74
	v_cvt_pk_bf16_f32 v83, v74, v75
	v_add_f32_e32 v72, v73, v72
	v_mul_f32_e32 v73, v69, v69
	v_mul_f32_e32 v74, v71, v71
	v_fmac_f32_e32 v73, v68, v68
	v_fmac_f32_e32 v74, v70, v70
	v_add_f32_e32 v73, v73, v74
	v_mul_f32_e32 v74, v65, v65
	v_fmac_f32_e32 v74, v64, v64
	v_add_f32_e32 v73, v74, v73
	v_mul_f32_e32 v74, v67, v67
	v_fmac_f32_e32 v74, v66, v66
	v_add_f32_e32 v73, v74, v73
	v_add_f32_e32 v72, v72, v73
	ds_bpermute_b32 v73, v217, v72
	v_lshlrev_b64 v[84:85], 1, v[84:85]
	v_cvt_pk_bf16_f32 v81, v78, v79
	v_lshl_add_u64 v[88:89], s[20:21], 0, v[84:85]
	global_store_dwordx4 v[88:89], v[80:83], off
	global_store_dwordx4 v[86:87], v[68:71], off offset:512
	global_store_dwordx4 v[86:87], v[64:67], off offset:528
	v_or_b32_e32 v84, 0x100, v84
	v_cvt_pk_bf16_f32 v68, v68, v69
	v_cvt_pk_bf16_f32 v69, v70, v71
	v_cvt_pk_bf16_f32 v70, v64, v65
	s_waitcnt lgkmcnt(0)
	v_add_f32_e32 v64, v72, v73
	ds_bpermute_b32 v65, v216, v64
	v_cvt_pk_bf16_f32 v71, v66, v67
	v_lshl_add_u64 v[66:67], s[20:21], 0, v[84:85]
	global_store_dwordx4 v[66:67], v[68:71], off
	s_and_saveexec_b64 s[24:25], s[4:5]
	s_cbranch_execz .LBB0_375
	v_lshlrev_b64 v[66:67], 6, v[206:207]
	v_lshl_add_u64 v[66:67], s[22:23], 0, v[66:67]
	v_lshl_add_u64 v[66:67], s[36:37], 2, v[66:67]
	s_lshl_b32 s90, s59, 2
	v_lshl_add_u64 v[66:67], v[66:67], 0, s[90:91]
	s_waitcnt lgkmcnt(0)
	v_add_f32_e32 v64, v64, v65
	global_store_dword v[66:67], v64, off
.LBB0_375:
	s_or_b64 exec, exec, s[24:25]
	s_waitcnt vmcnt(21)
	v_pk_fma_f32 v[62:63], v[62:63], 0.5, v[250:251] op_sel_hi:[1,0,1]
	v_pk_fma_f32 v[60:61], v[60:61], 0.5, v[248:249] op_sel_hi:[1,0,1]
	v_pk_fma_f32 v[58:59], v[58:59], 0.5, v[220:221] op_sel_hi:[1,0,1]
	v_pk_fma_f32 v[56:57], v[56:57], 0.5, v[218:219] op_sel_hi:[1,0,1]
	v_pk_fma_f32 v[54:55], v[54:55], 0.5, v[240:241] op_sel_hi:[1,0,1]
	v_pk_fma_f32 v[52:53], v[52:53], 0.5, v[238:239] op_sel_hi:[1,0,1]
	v_pk_fma_f32 v[48:49], v[48:49], 0.5, v[234:235] op_sel_hi:[1,0,1]
	v_pk_fma_f32 v[50:51], v[50:51], 0.5, v[236:237] op_sel_hi:[1,0,1]
	v_pk_fma_f32 v[46:47], v[46:47], 0.5, v[176:177] op_sel_hi:[1,0,1]
	v_pk_fma_f32 v[44:45], v[44:45], 0.5, v[174:175] op_sel_hi:[1,0,1]
	v_pk_fma_f32 v[42:43], v[42:43], 0.5, v[172:173] op_sel_hi:[1,0,1]
	v_pk_fma_f32 v[40:41], v[40:41], 0.5, v[170:171] op_sel_hi:[1,0,1]
	v_pk_fma_f32 v[38:39], v[38:39], 0.5, v[168:169] op_sel_hi:[1,0,1]
	v_pk_fma_f32 v[36:37], v[36:37], 0.5, v[166:167] op_sel_hi:[1,0,1]
	v_pk_fma_f32 v[32:33], v[32:33], 0.5, v[162:163] op_sel_hi:[1,0,1]
	v_pk_fma_f32 v[34:35], v[34:35], 0.5, v[164:165] op_sel_hi:[1,0,1]
	v_pk_fma_f32 v[30:31], v[30:31], 0.5, v[160:161] op_sel_hi:[1,0,1]
	v_pk_fma_f32 v[28:29], v[28:29], 0.5, v[158:159] op_sel_hi:[1,0,1]
	v_pk_fma_f32 v[26:27], v[26:27], 0.5, v[156:157] op_sel_hi:[1,0,1]
	v_pk_fma_f32 v[24:25], v[24:25], 0.5, v[154:155] op_sel_hi:[1,0,1]
	v_pk_fma_f32 v[22:23], v[22:23], 0.5, v[152:153] op_sel_hi:[1,0,1]
	v_pk_fma_f32 v[20:21], v[20:21], 0.5, v[150:151] op_sel_hi:[1,0,1]
	v_pk_fma_f32 v[16:17], v[16:17], 0.5, v[146:147] op_sel_hi:[1,0,1]
	v_pk_fma_f32 v[18:19], v[18:19], 0.5, v[148:149] op_sel_hi:[1,0,1]
	v_pk_fma_f32 v[14:15], v[14:15], 0.5, v[144:145] op_sel_hi:[1,0,1]
	v_pk_fma_f32 v[12:13], v[12:13], 0.5, v[142:143] op_sel_hi:[1,0,1]
	v_pk_fma_f32 v[10:11], v[10:11], 0.5, v[140:141] op_sel_hi:[1,0,1]
	v_pk_fma_f32 v[8:9], v[8:9], 0.5, v[138:139] op_sel_hi:[1,0,1]
	v_pk_fma_f32 v[6:7], v[6:7], 0.5, v[136:137] op_sel_hi:[1,0,1]
	v_pk_fma_f32 v[4:5], v[4:5], 0.5, v[134:135] op_sel_hi:[1,0,1]
	v_pk_fma_f32 v[0:1], v[0:1], 0.5, v[130:131] op_sel_hi:[1,0,1]
	v_pk_fma_f32 v[2:3], v[2:3], 0.5, v[132:133] op_sel_hi:[1,0,1]
	v_add_u32_e32 v120, 0x80, v202
	v_ashrrev_i32_e32 v121, 31, v120
	s_waitcnt lgkmcnt(0)
	v_add_u32_e32 v118, 0x90, v202
	v_ashrrev_i32_e32 v119, 31, v118
	v_add_u32_e32 v116, 0xa0, v202
	v_ashrrev_i32_e32 v117, 31, v116
	v_add_u32_e32 v114, 0xb0, v202
	v_ashrrev_i32_e32 v115, 31, v114
	v_lshlrev_b64 v[138:139], 10, v[120:121]
	v_lshl_add_u64 v[138:139], v[138:139], 0, v[200:201]
	v_lshl_add_u64 v[126:127], v[138:139], 2, s[14:15]
	global_store_dwordx4 v[126:127], v[60:63], off
	global_store_dwordx4 v[126:127], v[56:59], off offset:16
	v_cvt_pk_bf16_f32 v122, v60, v61
	v_mul_f32_e32 v61, v61, v61
	v_fmac_f32_e32 v61, v60, v60
	v_mul_f32_e32 v60, v63, v63
	v_cvt_pk_bf16_f32 v124, v56, v57
	v_fmac_f32_e32 v60, v62, v62
	v_mul_f32_e32 v57, v57, v57
	v_add_f32_e32 v60, v61, v60
	v_fmac_f32_e32 v57, v56, v56
	v_add_f32_e32 v56, v57, v60
	v_mul_f32_e32 v57, v59, v59
	v_fmac_f32_e32 v57, v58, v58
	v_cvt_pk_bf16_f32 v125, v58, v59
	v_add_f32_e32 v56, v57, v56
	v_mul_f32_e32 v57, v53, v53
	v_mul_f32_e32 v58, v55, v55
	v_fmac_f32_e32 v57, v52, v52
	v_fmac_f32_e32 v58, v54, v54
	v_add_f32_e32 v57, v57, v58
	v_mul_f32_e32 v58, v49, v49
	v_fmac_f32_e32 v58, v48, v48
	v_add_f32_e32 v57, v58, v57
	v_mul_f32_e32 v58, v51, v51
	v_fmac_f32_e32 v58, v50, v50
	v_add_f32_e32 v57, v58, v57
	v_add_f32_e32 v56, v56, v57
	ds_bpermute_b32 v57, v217, v56
	v_lshlrev_b64 v[128:129], 1, v[138:139]
	v_cvt_pk_bf16_f32 v123, v62, v63
	v_lshl_add_u64 v[138:139], s[20:21], 0, v[128:129]
	global_store_dwordx4 v[138:139], v[122:125], off
	global_store_dwordx4 v[126:127], v[52:55], off offset:512
	global_store_dwordx4 v[126:127], v[48:51], off offset:528
	v_or_b32_e32 v128, 0x100, v128
	v_cvt_pk_bf16_f32 v52, v52, v53
	v_cvt_pk_bf16_f32 v53, v54, v55
	v_cvt_pk_bf16_f32 v54, v48, v49
	s_waitcnt lgkmcnt(0)
	v_add_f32_e32 v48, v56, v57
	ds_bpermute_b32 v49, v216, v48
	v_cvt_pk_bf16_f32 v55, v50, v51
	v_lshl_add_u64 v[50:51], s[20:21], 0, v[128:129]
	global_store_dwordx4 v[50:51], v[52:55], off
	s_and_saveexec_b64 s[24:25], s[4:5]
	s_cbranch_execz .LBB0_377
	v_lshlrev_b64 v[50:51], 6, v[120:121]
	v_lshl_add_u64 v[50:51], s[22:23], 0, v[50:51]
	v_lshl_add_u64 v[50:51], s[36:37], 2, v[50:51]
	s_lshl_b32 s90, s59, 2
	v_lshl_add_u64 v[50:51], v[50:51], 0, s[90:91]
	s_waitcnt lgkmcnt(0)
	v_add_f32_e32 v48, v48, v49
	global_store_dword v[50:51], v48, off
.LBB0_377:
	s_or_b64 exec, exec, s[24:25]
	s_waitcnt lgkmcnt(0)
	v_lshlrev_b64 v[48:49], 10, v[118:119]
	v_lshl_add_u64 v[52:53], v[48:49], 0, v[200:201]
	v_lshl_add_u64 v[54:55], v[52:53], 2, s[14:15]
	global_store_dwordx4 v[54:55], v[44:47], off
	global_store_dwordx4 v[54:55], v[40:43], off offset:16
	v_cvt_pk_bf16_f32 v48, v44, v45
	v_mul_f32_e32 v45, v45, v45
	v_fmac_f32_e32 v45, v44, v44
	v_mul_f32_e32 v44, v47, v47
	v_cvt_pk_bf16_f32 v50, v40, v41
	v_fmac_f32_e32 v44, v46, v46
	v_mul_f32_e32 v41, v41, v41
	v_add_f32_e32 v44, v45, v44
	v_fmac_f32_e32 v41, v40, v40
	v_add_f32_e32 v40, v41, v44
	v_mul_f32_e32 v41, v43, v43
	v_fmac_f32_e32 v41, v42, v42
	v_cvt_pk_bf16_f32 v51, v42, v43
	v_add_f32_e32 v40, v41, v40
	v_mul_f32_e32 v41, v37, v37
	v_mul_f32_e32 v42, v39, v39
	v_fmac_f32_e32 v41, v36, v36
	v_fmac_f32_e32 v42, v38, v38
	v_add_f32_e32 v41, v41, v42
	v_mul_f32_e32 v42, v33, v33
	v_fmac_f32_e32 v42, v32, v32
	v_add_f32_e32 v41, v42, v41
	v_mul_f32_e32 v42, v35, v35
	v_fmac_f32_e32 v42, v34, v34
	v_add_f32_e32 v41, v42, v41
	v_add_f32_e32 v40, v40, v41
	ds_bpermute_b32 v41, v217, v40
	v_lshlrev_b64 v[52:53], 1, v[52:53]
	v_cvt_pk_bf16_f32 v49, v46, v47
	v_lshl_add_u64 v[56:57], s[20:21], 0, v[52:53]
	global_store_dwordx4 v[56:57], v[48:51], off
	global_store_dwordx4 v[54:55], v[36:39], off offset:512
	global_store_dwordx4 v[54:55], v[32:35], off offset:528
	v_or_b32_e32 v52, 0x100, v52
	v_cvt_pk_bf16_f32 v36, v36, v37
	v_cvt_pk_bf16_f32 v37, v38, v39
	v_cvt_pk_bf16_f32 v38, v32, v33
	s_waitcnt lgkmcnt(0)
	v_add_f32_e32 v32, v40, v41
	ds_bpermute_b32 v33, v216, v32
	v_cvt_pk_bf16_f32 v39, v34, v35
	v_lshl_add_u64 v[34:35], s[20:21], 0, v[52:53]
	global_store_dwordx4 v[34:35], v[36:39], off
	s_and_saveexec_b64 s[24:25], s[4:5]
	s_cbranch_execz .LBB0_379
	v_lshlrev_b64 v[34:35], 6, v[118:119]
	v_lshl_add_u64 v[34:35], s[22:23], 0, v[34:35]
	v_lshl_add_u64 v[34:35], s[36:37], 2, v[34:35]
	s_lshl_b32 s90, s59, 2
	v_lshl_add_u64 v[34:35], v[34:35], 0, s[90:91]
	s_waitcnt lgkmcnt(0)
	v_add_f32_e32 v32, v32, v33
	global_store_dword v[34:35], v32, off
.LBB0_379:
	s_or_b64 exec, exec, s[24:25]
	s_waitcnt lgkmcnt(0)
	v_lshlrev_b64 v[32:33], 10, v[116:117]
	v_lshl_add_u64 v[36:37], v[32:33], 0, v[200:201]
	v_lshl_add_u64 v[38:39], v[36:37], 2, s[14:15]
	global_store_dwordx4 v[38:39], v[28:31], off
	global_store_dwordx4 v[38:39], v[24:27], off offset:16
	v_cvt_pk_bf16_f32 v32, v28, v29
	v_mul_f32_e32 v29, v29, v29
	v_fmac_f32_e32 v29, v28, v28
	v_mul_f32_e32 v28, v31, v31
	v_cvt_pk_bf16_f32 v34, v24, v25
	v_fmac_f32_e32 v28, v30, v30
	v_mul_f32_e32 v25, v25, v25
	v_add_f32_e32 v28, v29, v28
	v_fmac_f32_e32 v25, v24, v24
	v_add_f32_e32 v24, v25, v28
	v_mul_f32_e32 v25, v27, v27
	v_fmac_f32_e32 v25, v26, v26
	v_cvt_pk_bf16_f32 v35, v26, v27
	v_add_f32_e32 v24, v25, v24
	v_mul_f32_e32 v25, v21, v21
	v_mul_f32_e32 v26, v23, v23
	v_fmac_f32_e32 v25, v20, v20
	v_fmac_f32_e32 v26, v22, v22
	v_add_f32_e32 v25, v25, v26
	v_mul_f32_e32 v26, v17, v17
	v_fmac_f32_e32 v26, v16, v16
	v_add_f32_e32 v25, v26, v25
	v_mul_f32_e32 v26, v19, v19
	v_fmac_f32_e32 v26, v18, v18
	v_add_f32_e32 v25, v26, v25
	v_add_f32_e32 v24, v24, v25
	ds_bpermute_b32 v25, v217, v24
	v_lshlrev_b64 v[36:37], 1, v[36:37]
	v_cvt_pk_bf16_f32 v33, v30, v31
	v_lshl_add_u64 v[40:41], s[20:21], 0, v[36:37]
	global_store_dwordx4 v[40:41], v[32:35], off
	global_store_dwordx4 v[38:39], v[20:23], off offset:512
	global_store_dwordx4 v[38:39], v[16:19], off offset:528
	v_or_b32_e32 v36, 0x100, v36
	v_cvt_pk_bf16_f32 v20, v20, v21
	v_cvt_pk_bf16_f32 v21, v22, v23
	v_cvt_pk_bf16_f32 v22, v16, v17
	s_waitcnt lgkmcnt(0)
	v_add_f32_e32 v16, v24, v25
	ds_bpermute_b32 v17, v216, v16
	v_cvt_pk_bf16_f32 v23, v18, v19
	v_lshl_add_u64 v[18:19], s[20:21], 0, v[36:37]
	global_store_dwordx4 v[18:19], v[20:23], off
	s_and_saveexec_b64 s[24:25], s[4:5]
	s_cbranch_execz .LBB0_381
	v_lshlrev_b64 v[18:19], 6, v[116:117]
	v_lshl_add_u64 v[18:19], s[22:23], 0, v[18:19]
	v_lshl_add_u64 v[18:19], s[36:37], 2, v[18:19]
	s_lshl_b32 s90, s59, 2
	v_lshl_add_u64 v[18:19], v[18:19], 0, s[90:91]
	s_waitcnt lgkmcnt(0)
	v_add_f32_e32 v16, v16, v17
	global_store_dword v[18:19], v16, off
.LBB0_381:
	s_or_b64 exec, exec, s[24:25]
	s_waitcnt lgkmcnt(0)
	v_lshlrev_b64 v[16:17], 10, v[114:115]
	v_lshl_add_u64 v[20:21], v[16:17], 0, v[200:201]
	v_lshl_add_u64 v[22:23], v[20:21], 2, s[14:15]
	global_store_dwordx4 v[22:23], v[12:15], off
	global_store_dwordx4 v[22:23], v[8:11], off offset:16
	v_cvt_pk_bf16_f32 v16, v12, v13
	v_mul_f32_e32 v13, v13, v13
	v_fmac_f32_e32 v13, v12, v12
	v_mul_f32_e32 v12, v15, v15
	v_cvt_pk_bf16_f32 v18, v8, v9
	v_fmac_f32_e32 v12, v14, v14
	v_mul_f32_e32 v9, v9, v9
	v_add_f32_e32 v12, v13, v12
	v_fmac_f32_e32 v9, v8, v8
	v_add_f32_e32 v8, v9, v12
	v_mul_f32_e32 v9, v11, v11
	v_fmac_f32_e32 v9, v10, v10
	v_cvt_pk_bf16_f32 v19, v10, v11
	v_add_f32_e32 v8, v9, v8
	v_mul_f32_e32 v9, v5, v5
	v_mul_f32_e32 v10, v7, v7
	v_fmac_f32_e32 v9, v4, v4
	v_fmac_f32_e32 v10, v6, v6
	v_add_f32_e32 v9, v9, v10
	v_mul_f32_e32 v10, v1, v1
	v_fmac_f32_e32 v10, v0, v0
	v_add_f32_e32 v9, v10, v9
	v_mul_f32_e32 v10, v3, v3
	v_fmac_f32_e32 v10, v2, v2
	v_add_f32_e32 v9, v10, v9
	v_add_f32_e32 v8, v8, v9
	ds_bpermute_b32 v9, v217, v8
	v_lshlrev_b64 v[20:21], 1, v[20:21]
	v_cvt_pk_bf16_f32 v17, v14, v15
	v_lshl_add_u64 v[24:25], s[20:21], 0, v[20:21]
	global_store_dwordx4 v[24:25], v[16:19], off
	global_store_dwordx4 v[22:23], v[4:7], off offset:512
	global_store_dwordx4 v[22:23], v[0:3], off offset:528
	v_or_b32_e32 v20, 0x100, v20
	v_cvt_pk_bf16_f32 v4, v4, v5
	v_cvt_pk_bf16_f32 v5, v6, v7
	v_cvt_pk_bf16_f32 v6, v0, v1
	s_waitcnt lgkmcnt(0)
	v_add_f32_e32 v0, v8, v9
	ds_bpermute_b32 v1, v216, v0
	v_cvt_pk_bf16_f32 v7, v2, v3
	v_lshl_add_u64 v[2:3], s[20:21], 0, v[20:21]
	global_store_dwordx4 v[2:3], v[4:7], off
	s_and_saveexec_b64 s[24:25], s[4:5]
	s_cbranch_execz .LBB0_383
	v_lshlrev_b64 v[2:3], 6, v[114:115]
	v_lshl_add_u64 v[2:3], s[22:23], 0, v[2:3]
	v_lshl_add_u64 v[2:3], s[36:37], 2, v[2:3]
	s_lshl_b32 s90, s59, 2
	v_lshl_add_u64 v[2:3], v[2:3], 0, s[90:91]
	s_waitcnt lgkmcnt(0)
	v_add_f32_e32 v0, v0, v1
	global_store_dword v[2:3], v0, off

.LBB0_1389:
	v_lshl_add_u32 v202, s42, 8, v212
	v_lshl_or_b32 v200, s40, 8, v214
	v_ashrrev_i32_e32 v201, 31, v200
	v_ashrrev_i32_e32 v203, 31, v202
	v_lshl_add_u64 v[204:205], v[200:201], 2, s[8:9]
	v_lshlrev_b64 v[130:131], 12, v[202:203]
	v_or_b32_e32 v210, 16, v202
	v_lshl_add_u64 v[130:131], v[204:205], 0, v[130:131]
	v_ashrrev_i32_e32 v211, 31, v210
	global_load_dwordx4 v[194:197], v[130:131], off offset:16
	global_load_dwordx4 v[218:221], v[130:131], off
	global_load_dwordx4 v[234:237], v[130:131], off offset:528
	global_load_dwordx4 v[238:241], v[130:131], off offset:512
	v_lshlrev_b64 v[130:131], 12, v[210:211]
	v_or_b32_e32 v208, 32, v202
	v_lshl_add_u64 v[130:131], v[204:205], 0, v[130:131]
	v_ashrrev_i32_e32 v209, 31, v208
	global_load_dwordx4 v[170:173], v[130:131], off offset:16
	global_load_dwordx4 v[174:177], v[130:131], off
	global_load_dwordx4 v[162:165], v[130:131], off offset:528
	global_load_dwordx4 v[166:169], v[130:131], off offset:512
	v_lshlrev_b64 v[130:131], 12, v[208:209]
	v_or_b32_e32 v206, 48, v202
	v_lshl_add_u64 v[130:131], v[204:205], 0, v[130:131]
	v_ashrrev_i32_e32 v207, 31, v206
	global_load_dwordx4 v[154:157], v[130:131], off offset:16
	global_load_dwordx4 v[158:161], v[130:131], off
	global_load_dwordx4 v[146:149], v[130:131], off offset:528
	global_load_dwordx4 v[150:153], v[130:131], off offset:512
	v_lshlrev_b64 v[130:131], 12, v[206:207]
	v_lshl_add_u64 v[134:135], v[204:205], 0, v[130:131]
	global_load_dwordx4 v[138:141], v[134:135], off offset:16
	global_load_dwordx4 v[142:145], v[134:135], off
	global_load_dwordx4 v[130:133], v[134:135], off offset:528
	s_nop 0
	global_load_dwordx4 v[134:137], v[134:135], off offset:512
	v_and_b32_e32 v217, 64, v245
	v_xor_b32_e32 v216, 16, v245
	v_add_u32_e32 v222, 64, v217
	v_cmp_lt_i32_e32 vcc, v216, v222
	s_lshl_b32 s40, s40, 2
	s_ashr_i32 s41, s40, 31
	v_cndmask_b32_e32 v216, v245, v216, vcc
	v_lshlrev_b32_e32 v217, 2, v216
	v_xor_b32_e32 v216, 32, v245
	v_cmp_lt_i32_e32 vcc, v216, v222
	s_nop 1
	v_cndmask_b32_e32 v216, v245, v216, vcc
	v_lshlrev_b32_e32 v216, 2, v216
	v_lshlrev_b64 v[222:223], 10, v[202:203]
	v_lshl_add_u64 v[222:223], v[222:223], 0, v[200:201]
	s_waitcnt vmcnt(0)
	v_pk_add_f32 v[128:129], v[128:129], v[220:221]
	v_pk_add_f32 v[126:127], v[126:127], v[218:219]
	v_pk_add_f32 v[124:125], v[124:125], v[196:197]
	v_pk_add_f32 v[122:123], v[122:123], v[194:195]
	v_pk_add_f32 v[120:121], v[120:121], v[240:241]
	v_pk_add_f32 v[118:119], v[118:119], v[238:239]
	v_pk_add_f32 v[114:115], v[114:115], v[234:235]
	v_pk_add_f32 v[116:117], v[116:117], v[236:237]
	v_pk_add_f32 v[110:111], v[110:111], v[176:177]
	v_pk_add_f32 v[108:109], v[108:109], v[174:175]
	v_pk_add_f32 v[106:107], v[106:107], v[172:173]
	v_pk_add_f32 v[104:105], v[104:105], v[170:171]
	v_pk_add_f32 v[102:103], v[102:103], v[168:169]
	v_pk_add_f32 v[100:101], v[100:101], v[166:167]
	v_pk_add_f32 v[96:97], v[96:97], v[162:163]
	v_pk_add_f32 v[98:99], v[98:99], v[164:165]
	v_pk_add_f32 v[94:95], v[94:95], v[160:161]
	v_pk_add_f32 v[92:93], v[92:93], v[158:159]
	v_pk_add_f32 v[90:91], v[90:91], v[156:157]
	v_pk_add_f32 v[88:89], v[88:89], v[154:155]
	v_pk_add_f32 v[86:87], v[86:87], v[152:153]
	v_pk_add_f32 v[84:85], v[84:85], v[150:151]
	v_pk_add_f32 v[80:81], v[80:81], v[146:147]
	v_pk_add_f32 v[82:83], v[82:83], v[148:149]
	v_pk_add_f32 v[78:79], v[78:79], v[144:145]
	v_pk_add_f32 v[76:77], v[76:77], v[142:143]
	v_pk_add_f32 v[74:75], v[74:75], v[140:141]
	v_pk_add_f32 v[72:73], v[72:73], v[138:139]
	v_pk_add_f32 v[70:71], v[70:71], v[136:137]
	v_pk_add_f32 v[68:69], v[68:69], v[134:135]
	v_pk_add_f32 v[64:65], v[64:65], v[130:131]
	v_pk_add_f32 v[66:67], v[66:67], v[132:133]
	v_lshl_add_u64 v[218:219], v[222:223], 2, s[10:11]
	global_store_dwordx4 v[218:219], v[126:129], off
	global_store_dwordx4 v[218:219], v[122:125], off offset:16
	v_cvt_pk_bf16_f32 v194, v126, v127
	v_mul_f32_e32 v127, v127, v127
	v_fmac_f32_e32 v127, v126, v126
	v_mul_f32_e32 v126, v129, v129
	v_cvt_pk_bf16_f32 v196, v122, v123
	v_fmac_f32_e32 v126, v128, v128
	v_mul_f32_e32 v123, v123, v123
	v_add_f32_e32 v126, v127, v126
	v_fmac_f32_e32 v123, v122, v122
	v_add_f32_e32 v122, v123, v126
	v_mul_f32_e32 v123, v125, v125
	v_fmac_f32_e32 v123, v124, v124
	v_cvt_pk_bf16_f32 v197, v124, v125
	v_add_f32_e32 v122, v123, v122
	v_mul_f32_e32 v123, v119, v119
	v_mul_f32_e32 v124, v121, v121
	v_fmac_f32_e32 v123, v118, v118
	v_fmac_f32_e32 v124, v120, v120
	v_add_f32_e32 v123, v123, v124
	v_mul_f32_e32 v124, v115, v115
	v_fmac_f32_e32 v124, v114, v114
	v_add_f32_e32 v123, v124, v123
	v_mul_f32_e32 v124, v117, v117
	v_fmac_f32_e32 v124, v116, v116
	v_add_f32_e32 v123, v124, v123
	v_add_f32_e32 v122, v122, v123
	ds_bpermute_b32 v123, v217, v122
	v_lshlrev_b64 v[220:221], 1, v[222:223]
	v_cvt_pk_bf16_f32 v195, v128, v129
	v_lshl_add_u64 v[222:223], s[16:17], 0, v[220:221]
	global_store_dwordx4 v[222:223], v[194:197], off
	global_store_dwordx4 v[218:219], v[118:121], off offset:512
	global_store_dwordx4 v[218:219], v[114:117], off offset:528
	v_or_b32_e32 v220, 0x100, v220
	v_cvt_pk_bf16_f32 v118, v118, v119
	v_cvt_pk_bf16_f32 v119, v120, v121
	v_cvt_pk_bf16_f32 v120, v114, v115
	s_waitcnt lgkmcnt(0)
	v_add_f32_e32 v114, v122, v123
	ds_bpermute_b32 v115, v216, v114
	v_cvt_pk_bf16_f32 v121, v116, v117
	v_lshl_add_u64 v[116:117], s[16:17], 0, v[220:221]
	v_add_u32_e32 v238, 0x80, v202
	v_ashrrev_i32_e32 v239, 31, v238
	v_lshlrev_b64 v[238:239], 12, v[238:239]
	v_lshl_add_u64 v[238:239], v[204:205], 0, v[238:239]
	global_load_dwordx4 v[194:197], v[238:239], off offset:16
	global_load_dwordx4 v[218:221], v[238:239], off
	global_load_dwordx4 v[234:237], v[238:239], off offset:528
	s_nop 0
	global_load_dwordx4 v[238:241], v[238:239], off offset:512
	v_add_u32_e32 v166, 0x80, v210
	v_ashrrev_i32_e32 v167, 31, v166
	v_lshlrev_b64 v[166:167], 12, v[166:167]
	v_lshl_add_u64 v[166:167], v[204:205], 0, v[166:167]
	global_load_dwordx4 v[170:173], v[166:167], off offset:16
	global_load_dwordx4 v[174:177], v[166:167], off
	global_load_dwordx4 v[162:165], v[166:167], off offset:528
	s_nop 0
	global_load_dwordx4 v[166:169], v[166:167], off offset:512
	v_add_u32_e32 v150, 0x80, v208
	v_ashrrev_i32_e32 v151, 31, v150
	v_lshlrev_b64 v[150:151], 12, v[150:151]
	v_lshl_add_u64 v[150:151], v[204:205], 0, v[150:151]
	global_load_dwordx4 v[154:157], v[150:151], off offset:16
	global_load_dwordx4 v[158:161], v[150:151], off
	global_load_dwordx4 v[146:149], v[150:151], off offset:528
	s_nop 0
	global_load_dwordx4 v[150:153], v[150:151], off offset:512
	v_add_u32_e32 v134, 0x80, v206
	v_ashrrev_i32_e32 v135, 31, v134
	v_lshlrev_b64 v[134:135], 12, v[134:135]
	v_lshl_add_u64 v[134:135], v[204:205], 0, v[134:135]
	global_load_dwordx4 v[138:141], v[134:135], off offset:16
	global_load_dwordx4 v[142:145], v[134:135], off
	global_load_dwordx4 v[130:133], v[134:135], off offset:528
	s_nop 0
	global_load_dwordx4 v[134:137], v[134:135], off offset:512
	global_store_dwordx4 v[116:117], v[118:121], off
	s_and_saveexec_b64 s[24:25], s[4:5]
	s_movk_i32 s84, 0x90
	s_movk_i32 s85, 0xaff
	s_cbranch_execz .LBB0_1391
	v_lshlrev_b64 v[116:117], 6, v[202:203]
	v_lshl_add_u64 v[116:117], s[18:19], 0, v[116:117]
	v_lshl_add_u64 v[116:117], s[40:41], 2, v[116:117]
	s_lshl_b32 s90, s71, 2
	v_lshl_add_u64 v[116:117], v[116:117], 0, s[90:91]
	s_waitcnt lgkmcnt(0)
	v_add_f32_e32 v114, v114, v115
	global_store_dword v[116:117], v114, off
.LBB0_1391:
	s_or_b64 exec, exec, s[24:25]
	s_waitcnt lgkmcnt(0)
	v_lshlrev_b64 v[114:115], 10, v[210:211]
	v_lshl_add_u64 v[118:119], v[114:115], 0, v[200:201]
	v_lshl_add_u64 v[120:121], v[118:119], 2, s[10:11]
	global_store_dwordx4 v[120:121], v[108:111], off
	global_store_dwordx4 v[120:121], v[104:107], off offset:16
	v_cvt_pk_bf16_f32 v114, v108, v109
	v_mul_f32_e32 v109, v109, v109
	v_fmac_f32_e32 v109, v108, v108
	v_mul_f32_e32 v108, v111, v111
	v_cvt_pk_bf16_f32 v116, v104, v105
	v_fmac_f32_e32 v108, v110, v110
	v_mul_f32_e32 v105, v105, v105
	v_add_f32_e32 v108, v109, v108
	v_fmac_f32_e32 v105, v104, v104
	v_add_f32_e32 v104, v105, v108
	v_mul_f32_e32 v105, v107, v107
	v_fmac_f32_e32 v105, v106, v106
	v_cvt_pk_bf16_f32 v117, v106, v107
	v_add_f32_e32 v104, v105, v104
	v_mul_f32_e32 v105, v101, v101
	v_mul_f32_e32 v106, v103, v103
	v_fmac_f32_e32 v105, v100, v100
	v_fmac_f32_e32 v106, v102, v102
	v_add_f32_e32 v105, v105, v106
	v_mul_f32_e32 v106, v97, v97
	v_fmac_f32_e32 v106, v96, v96
	v_add_f32_e32 v105, v106, v105
	v_mul_f32_e32 v106, v99, v99
	v_fmac_f32_e32 v106, v98, v98
	v_add_f32_e32 v105, v106, v105
	v_add_f32_e32 v104, v104, v105
	ds_bpermute_b32 v105, v217, v104
	v_lshlrev_b64 v[118:119], 1, v[118:119]
	v_cvt_pk_bf16_f32 v115, v110, v111
	v_lshl_add_u64 v[122:123], s[16:17], 0, v[118:119]
	global_store_dwordx4 v[122:123], v[114:117], off
	global_store_dwordx4 v[120:121], v[100:103], off offset:512
	global_store_dwordx4 v[120:121], v[96:99], off offset:528
	v_or_b32_e32 v118, 0x100, v118
	v_cvt_pk_bf16_f32 v100, v100, v101
	v_cvt_pk_bf16_f32 v101, v102, v103
	v_cvt_pk_bf16_f32 v102, v96, v97
	s_waitcnt lgkmcnt(0)
	v_add_f32_e32 v96, v104, v105
	ds_bpermute_b32 v97, v216, v96
	v_cvt_pk_bf16_f32 v103, v98, v99
	v_lshl_add_u64 v[98:99], s[16:17], 0, v[118:119]
	global_store_dwordx4 v[98:99], v[100:103], off
	s_and_saveexec_b64 s[24:25], s[4:5]
	s_cbranch_execz .LBB0_1393
	v_lshlrev_b64 v[98:99], 6, v[210:211]
	v_lshl_add_u64 v[98:99], s[18:19], 0, v[98:99]
	v_lshl_add_u64 v[98:99], s[40:41], 2, v[98:99]
	s_lshl_b32 s90, s71, 2
	v_lshl_add_u64 v[98:99], v[98:99], 0, s[90:91]
	s_waitcnt lgkmcnt(0)
	v_add_f32_e32 v96, v96, v97
	global_store_dword v[98:99], v96, off
.LBB0_1393:
	s_or_b64 exec, exec, s[24:25]
	s_waitcnt lgkmcnt(0)
	v_lshlrev_b64 v[96:97], 10, v[208:209]
	v_lshl_add_u64 v[100:101], v[96:97], 0, v[200:201]
	v_lshl_add_u64 v[102:103], v[100:101], 2, s[10:11]
	global_store_dwordx4 v[102:103], v[92:95], off
	global_store_dwordx4 v[102:103], v[88:91], off offset:16
	v_cvt_pk_bf16_f32 v96, v92, v93
	v_mul_f32_e32 v93, v93, v93
	v_fmac_f32_e32 v93, v92, v92
	v_mul_f32_e32 v92, v95, v95
	v_cvt_pk_bf16_f32 v98, v88, v89
	v_fmac_f32_e32 v92, v94, v94
	v_mul_f32_e32 v89, v89, v89
	v_add_f32_e32 v92, v93, v92
	v_fmac_f32_e32 v89, v88, v88
	v_add_f32_e32 v88, v89, v92
	v_mul_f32_e32 v89, v91, v91
	v_fmac_f32_e32 v89, v90, v90
	v_cvt_pk_bf16_f32 v99, v90, v91
	v_add_f32_e32 v88, v89, v88
	v_mul_f32_e32 v89, v85, v85
	v_mul_f32_e32 v90, v87, v87
	v_fmac_f32_e32 v89, v84, v84
	v_fmac_f32_e32 v90, v86, v86
	v_add_f32_e32 v89, v89, v90
	v_mul_f32_e32 v90, v81, v81
	v_fmac_f32_e32 v90, v80, v80
	v_add_f32_e32 v89, v90, v89
	v_mul_f32_e32 v90, v83, v83
	v_fmac_f32_e32 v90, v82, v82
	v_add_f32_e32 v89, v90, v89
	v_add_f32_e32 v88, v88, v89
	ds_bpermute_b32 v89, v217, v88
	v_lshlrev_b64 v[100:101], 1, v[100:101]
	v_cvt_pk_bf16_f32 v97, v94, v95
	v_lshl_add_u64 v[104:105], s[16:17], 0, v[100:101]
	global_store_dwordx4 v[104:105], v[96:99], off
	global_store_dwordx4 v[102:103], v[84:87], off offset:512
	global_store_dwordx4 v[102:103], v[80:83], off offset:528
	v_or_b32_e32 v100, 0x100, v100
	v_cvt_pk_bf16_f32 v84, v84, v85
	v_cvt_pk_bf16_f32 v85, v86, v87
	v_cvt_pk_bf16_f32 v86, v80, v81
	s_waitcnt lgkmcnt(0)
	v_add_f32_e32 v80, v88, v89
	ds_bpermute_b32 v81, v216, v80
	v_cvt_pk_bf16_f32 v87, v82, v83
	v_lshl_add_u64 v[82:83], s[16:17], 0, v[100:101]
	global_store_dwordx4 v[82:83], v[84:87], off
	s_and_saveexec_b64 s[24:25], s[4:5]
	v_readlane_b32 s62, v255, 36
	v_readlane_b32 s63, v255, 37
	s_cbranch_execz .LBB0_1395
	v_lshlrev_b64 v[82:83], 6, v[208:209]
	v_lshl_add_u64 v[82:83], s[18:19], 0, v[82:83]
	v_lshl_add_u64 v[82:83], s[40:41], 2, v[82:83]
	s_lshl_b32 s90, s71, 2
	v_lshl_add_u64 v[82:83], v[82:83], 0, s[90:91]
	s_waitcnt lgkmcnt(0)
	v_add_f32_e32 v80, v80, v81
	global_store_dword v[82:83], v80, off
.LBB0_1395:
	s_or_b64 exec, exec, s[24:25]
	s_waitcnt lgkmcnt(0)
	v_lshlrev_b64 v[80:81], 10, v[206:207]
	v_lshl_add_u64 v[84:85], v[80:81], 0, v[200:201]
	v_lshl_add_u64 v[86:87], v[84:85], 2, s[10:11]
	global_store_dwordx4 v[86:87], v[76:79], off
	global_store_dwordx4 v[86:87], v[72:75], off offset:16
	v_cvt_pk_bf16_f32 v80, v76, v77
	v_mul_f32_e32 v77, v77, v77
	v_fmac_f32_e32 v77, v76, v76
	v_mul_f32_e32 v76, v79, v79
	v_cvt_pk_bf16_f32 v82, v72, v73
	v_fmac_f32_e32 v76, v78, v78
	v_mul_f32_e32 v73, v73, v73
	v_add_f32_e32 v76, v77, v76
	v_fmac_f32_e32 v73, v72, v72
	v_add_f32_e32 v72, v73, v76
	v_mul_f32_e32 v73, v75, v75
	v_fmac_f32_e32 v73, v74, v74
	v_cvt_pk_bf16_f32 v83, v74, v75
	v_add_f32_e32 v72, v73, v72
	v_mul_f32_e32 v73, v69, v69
	v_mul_f32_e32 v74, v71, v71
	v_fmac_f32_e32 v73, v68, v68
	v_fmac_f32_e32 v74, v70, v70
	v_add_f32_e32 v73, v73, v74
	v_mul_f32_e32 v74, v65, v65
	v_fmac_f32_e32 v74, v64, v64
	v_add_f32_e32 v73, v74, v73
	v_mul_f32_e32 v74, v67, v67
	v_fmac_f32_e32 v74, v66, v66
	v_add_f32_e32 v73, v74, v73
	v_add_f32_e32 v72, v72, v73
	ds_bpermute_b32 v73, v217, v72
	v_lshlrev_b64 v[84:85], 1, v[84:85]
	v_cvt_pk_bf16_f32 v81, v78, v79
	v_lshl_add_u64 v[88:89], s[16:17], 0, v[84:85]
	global_store_dwordx4 v[88:89], v[80:83], off
	global_store_dwordx4 v[86:87], v[68:71], off offset:512
	global_store_dwordx4 v[86:87], v[64:67], off offset:528
	v_or_b32_e32 v84, 0x100, v84
	v_cvt_pk_bf16_f32 v68, v68, v69
	v_cvt_pk_bf16_f32 v69, v70, v71
	v_cvt_pk_bf16_f32 v70, v64, v65
	s_waitcnt lgkmcnt(0)
	v_add_f32_e32 v64, v72, v73
	ds_bpermute_b32 v65, v216, v64
	v_cvt_pk_bf16_f32 v71, v66, v67
	v_lshl_add_u64 v[66:67], s[16:17], 0, v[84:85]
	global_store_dwordx4 v[66:67], v[68:71], off
	s_and_saveexec_b64 s[24:25], s[4:5]
	s_cbranch_execz .LBB0_1397
	v_lshlrev_b64 v[66:67], 6, v[206:207]
	v_lshl_add_u64 v[66:67], s[18:19], 0, v[66:67]
	v_lshl_add_u64 v[66:67], s[40:41], 2, v[66:67]
	s_lshl_b32 s90, s71, 2
	v_lshl_add_u64 v[66:67], v[66:67], 0, s[90:91]
	s_waitcnt lgkmcnt(0)
	v_add_f32_e32 v64, v64, v65
	global_store_dword v[66:67], v64, off
.LBB0_1397:
	s_or_b64 exec, exec, s[24:25]
	s_waitcnt vmcnt(19)
	v_pk_add_f32 v[62:63], v[62:63], v[220:221]
	v_pk_add_f32 v[60:61], v[60:61], v[218:219]
	v_pk_add_f32 v[58:59], v[58:59], v[196:197]
	v_pk_add_f32 v[56:57], v[56:57], v[194:195]
	v_pk_add_f32 v[54:55], v[54:55], v[240:241]
	v_pk_add_f32 v[52:53], v[52:53], v[238:239]
	v_pk_add_f32 v[48:49], v[48:49], v[234:235]
	v_pk_add_f32 v[50:51], v[50:51], v[236:237]
	v_pk_add_f32 v[46:47], v[46:47], v[176:177]
	v_pk_add_f32 v[44:45], v[44:45], v[174:175]
	v_pk_add_f32 v[42:43], v[42:43], v[172:173]
	v_pk_add_f32 v[40:41], v[40:41], v[170:171]
	v_pk_add_f32 v[38:39], v[38:39], v[168:169]
	v_pk_add_f32 v[36:37], v[36:37], v[166:167]
	v_pk_add_f32 v[32:33], v[32:33], v[162:163]
	v_pk_add_f32 v[34:35], v[34:35], v[164:165]
	v_pk_add_f32 v[30:31], v[30:31], v[160:161]
	v_pk_add_f32 v[28:29], v[28:29], v[158:159]
	v_pk_add_f32 v[26:27], v[26:27], v[156:157]
	v_pk_add_f32 v[24:25], v[24:25], v[154:155]
	v_pk_add_f32 v[22:23], v[22:23], v[152:153]
	v_pk_add_f32 v[20:21], v[20:21], v[150:151]
	v_pk_add_f32 v[16:17], v[16:17], v[146:147]
	v_pk_add_f32 v[18:19], v[18:19], v[148:149]
	v_pk_add_f32 v[14:15], v[14:15], v[144:145]
	v_pk_add_f32 v[12:13], v[12:13], v[142:143]
	v_pk_add_f32 v[10:11], v[10:11], v[140:141]
	v_pk_add_f32 v[8:9], v[8:9], v[138:139]
	v_pk_add_f32 v[6:7], v[6:7], v[136:137]
	v_pk_add_f32 v[4:5], v[4:5], v[134:135]
	v_pk_add_f32 v[0:1], v[0:1], v[130:131]
	v_pk_add_f32 v[2:3], v[2:3], v[132:133]
	v_add_u32_e32 v120, 0x80, v202
	v_ashrrev_i32_e32 v121, 31, v120
	s_waitcnt lgkmcnt(0)
	v_add_u32_e32 v118, 0x90, v202
	v_ashrrev_i32_e32 v119, 31, v118
	v_add_u32_e32 v116, 0xa0, v202
	v_ashrrev_i32_e32 v117, 31, v116
	v_add_u32_e32 v114, 0xb0, v202
	v_ashrrev_i32_e32 v115, 31, v114
	v_lshlrev_b64 v[138:139], 10, v[120:121]
	v_lshl_add_u64 v[138:139], v[138:139], 0, v[200:201]
	v_lshl_add_u64 v[126:127], v[138:139], 2, s[10:11]
	global_store_dwordx4 v[126:127], v[60:63], off
	global_store_dwordx4 v[126:127], v[56:59], off offset:16
	v_cvt_pk_bf16_f32 v122, v60, v61
	v_mul_f32_e32 v61, v61, v61
	v_fmac_f32_e32 v61, v60, v60
	v_mul_f32_e32 v60, v63, v63
	v_cvt_pk_bf16_f32 v124, v56, v57
	v_fmac_f32_e32 v60, v62, v62
	v_mul_f32_e32 v57, v57, v57
	v_add_f32_e32 v60, v61, v60
	v_fmac_f32_e32 v57, v56, v56
	v_add_f32_e32 v56, v57, v60
	v_mul_f32_e32 v57, v59, v59
	v_fmac_f32_e32 v57, v58, v58
	v_cvt_pk_bf16_f32 v125, v58, v59
	v_add_f32_e32 v56, v57, v56
	v_mul_f32_e32 v57, v53, v53
	v_mul_f32_e32 v58, v55, v55
	v_fmac_f32_e32 v57, v52, v52
	v_fmac_f32_e32 v58, v54, v54
	v_add_f32_e32 v57, v57, v58
	v_mul_f32_e32 v58, v49, v49
	v_fmac_f32_e32 v58, v48, v48
	v_add_f32_e32 v57, v58, v57
	v_mul_f32_e32 v58, v51, v51
	v_fmac_f32_e32 v58, v50, v50
	v_add_f32_e32 v57, v58, v57
	v_add_f32_e32 v56, v56, v57
	ds_bpermute_b32 v57, v217, v56
	v_lshlrev_b64 v[128:129], 1, v[138:139]
	v_cvt_pk_bf16_f32 v123, v62, v63
	v_lshl_add_u64 v[138:139], s[16:17], 0, v[128:129]
	global_store_dwordx4 v[138:139], v[122:125], off
	global_store_dwordx4 v[126:127], v[52:55], off offset:512
	global_store_dwordx4 v[126:127], v[48:51], off offset:528
	v_or_b32_e32 v128, 0x100, v128
	v_cvt_pk_bf16_f32 v52, v52, v53
	v_cvt_pk_bf16_f32 v53, v54, v55
	v_cvt_pk_bf16_f32 v54, v48, v49
	s_waitcnt lgkmcnt(0)
	v_add_f32_e32 v48, v56, v57
	ds_bpermute_b32 v49, v216, v48
	v_cvt_pk_bf16_f32 v55, v50, v51
	v_lshl_add_u64 v[50:51], s[16:17], 0, v[128:129]
	global_store_dwordx4 v[50:51], v[52:55], off
	s_and_saveexec_b64 s[24:25], s[4:5]
	s_cbranch_execz .LBB0_1399
	v_lshlrev_b64 v[50:51], 6, v[120:121]
	v_lshl_add_u64 v[50:51], s[18:19], 0, v[50:51]
	v_lshl_add_u64 v[50:51], s[40:41], 2, v[50:51]
	s_lshl_b32 s90, s71, 2
	v_lshl_add_u64 v[50:51], v[50:51], 0, s[90:91]
	s_waitcnt lgkmcnt(0)
	v_add_f32_e32 v48, v48, v49
	global_store_dword v[50:51], v48, off
.LBB0_1399:
	s_or_b64 exec, exec, s[24:25]
	s_waitcnt lgkmcnt(0)
	v_lshlrev_b64 v[48:49], 10, v[118:119]
	v_lshl_add_u64 v[52:53], v[48:49], 0, v[200:201]
	v_lshl_add_u64 v[54:55], v[52:53], 2, s[10:11]
	global_store_dwordx4 v[54:55], v[44:47], off
	global_store_dwordx4 v[54:55], v[40:43], off offset:16
	v_cvt_pk_bf16_f32 v48, v44, v45
	v_mul_f32_e32 v45, v45, v45
	v_fmac_f32_e32 v45, v44, v44
	v_mul_f32_e32 v44, v47, v47
	v_cvt_pk_bf16_f32 v50, v40, v41
	v_fmac_f32_e32 v44, v46, v46
	v_mul_f32_e32 v41, v41, v41
	v_add_f32_e32 v44, v45, v44
	v_fmac_f32_e32 v41, v40, v40
	v_add_f32_e32 v40, v41, v44
	v_mul_f32_e32 v41, v43, v43
	v_fmac_f32_e32 v41, v42, v42
	v_cvt_pk_bf16_f32 v51, v42, v43
	v_add_f32_e32 v40, v41, v40
	v_mul_f32_e32 v41, v37, v37
	v_mul_f32_e32 v42, v39, v39
	v_fmac_f32_e32 v41, v36, v36
	v_fmac_f32_e32 v42, v38, v38
	v_add_f32_e32 v41, v41, v42
	v_mul_f32_e32 v42, v33, v33
	v_fmac_f32_e32 v42, v32, v32
	v_add_f32_e32 v41, v42, v41
	v_mul_f32_e32 v42, v35, v35
	v_fmac_f32_e32 v42, v34, v34
	v_add_f32_e32 v41, v42, v41
	v_add_f32_e32 v40, v40, v41
	ds_bpermute_b32 v41, v217, v40
	v_lshlrev_b64 v[52:53], 1, v[52:53]
	v_cvt_pk_bf16_f32 v49, v46, v47
	v_lshl_add_u64 v[56:57], s[16:17], 0, v[52:53]
	global_store_dwordx4 v[56:57], v[48:51], off
	global_store_dwordx4 v[54:55], v[36:39], off offset:512
	global_store_dwordx4 v[54:55], v[32:35], off offset:528
	v_or_b32_e32 v52, 0x100, v52
	v_cvt_pk_bf16_f32 v36, v36, v37
	v_cvt_pk_bf16_f32 v37, v38, v39
	v_cvt_pk_bf16_f32 v38, v32, v33
	s_waitcnt lgkmcnt(0)
	v_add_f32_e32 v32, v40, v41
	ds_bpermute_b32 v33, v216, v32
	v_cvt_pk_bf16_f32 v39, v34, v35
	v_lshl_add_u64 v[34:35], s[16:17], 0, v[52:53]
	global_store_dwordx4 v[34:35], v[36:39], off
	s_and_saveexec_b64 s[24:25], s[4:5]
	s_cbranch_execz .LBB0_1401
	v_lshlrev_b64 v[34:35], 6, v[118:119]
	v_lshl_add_u64 v[34:35], s[18:19], 0, v[34:35]
	v_lshl_add_u64 v[34:35], s[40:41], 2, v[34:35]
	s_lshl_b32 s90, s71, 2
	v_lshl_add_u64 v[34:35], v[34:35], 0, s[90:91]
	s_waitcnt lgkmcnt(0)
	v_add_f32_e32 v32, v32, v33
	global_store_dword v[34:35], v32, off
.LBB0_1401:
	s_or_b64 exec, exec, s[24:25]
	s_waitcnt lgkmcnt(0)
	v_lshlrev_b64 v[32:33], 10, v[116:117]
	v_lshl_add_u64 v[36:37], v[32:33], 0, v[200:201]
	v_lshl_add_u64 v[38:39], v[36:37], 2, s[10:11]
	global_store_dwordx4 v[38:39], v[28:31], off
	global_store_dwordx4 v[38:39], v[24:27], off offset:16
	v_cvt_pk_bf16_f32 v32, v28, v29
	v_mul_f32_e32 v29, v29, v29
	v_fmac_f32_e32 v29, v28, v28
	v_mul_f32_e32 v28, v31, v31
	v_cvt_pk_bf16_f32 v34, v24, v25
	v_fmac_f32_e32 v28, v30, v30
	v_mul_f32_e32 v25, v25, v25
	v_add_f32_e32 v28, v29, v28
	v_fmac_f32_e32 v25, v24, v24
	v_add_f32_e32 v24, v25, v28
	v_mul_f32_e32 v25, v27, v27
	v_fmac_f32_e32 v25, v26, v26
	v_cvt_pk_bf16_f32 v35, v26, v27
	v_add_f32_e32 v24, v25, v24
	v_mul_f32_e32 v25, v21, v21
	v_mul_f32_e32 v26, v23, v23
	v_fmac_f32_e32 v25, v20, v20
	v_fmac_f32_e32 v26, v22, v22
	v_add_f32_e32 v25, v25, v26
	v_mul_f32_e32 v26, v17, v17
	v_fmac_f32_e32 v26, v16, v16
	v_add_f32_e32 v25, v26, v25
	v_mul_f32_e32 v26, v19, v19
	v_fmac_f32_e32 v26, v18, v18
	v_add_f32_e32 v25, v26, v25
	v_add_f32_e32 v24, v24, v25
	ds_bpermute_b32 v25, v217, v24
	v_lshlrev_b64 v[36:37], 1, v[36:37]
	v_cvt_pk_bf16_f32 v33, v30, v31
	v_lshl_add_u64 v[40:41], s[16:17], 0, v[36:37]
	global_store_dwordx4 v[40:41], v[32:35], off
	global_store_dwordx4 v[38:39], v[20:23], off offset:512
	global_store_dwordx4 v[38:39], v[16:19], off offset:528
	v_or_b32_e32 v36, 0x100, v36
	v_cvt_pk_bf16_f32 v20, v20, v21
	v_cvt_pk_bf16_f32 v21, v22, v23
	v_cvt_pk_bf16_f32 v22, v16, v17
	s_waitcnt lgkmcnt(0)
	v_add_f32_e32 v16, v24, v25
	ds_bpermute_b32 v17, v216, v16
	v_cvt_pk_bf16_f32 v23, v18, v19
	v_lshl_add_u64 v[18:19], s[16:17], 0, v[36:37]
	global_store_dwordx4 v[18:19], v[20:23], off
	s_and_saveexec_b64 s[24:25], s[4:5]
	s_cbranch_execz .LBB0_1403
	v_lshlrev_b64 v[18:19], 6, v[116:117]
	v_lshl_add_u64 v[18:19], s[18:19], 0, v[18:19]
	v_lshl_add_u64 v[18:19], s[40:41], 2, v[18:19]
	s_lshl_b32 s90, s71, 2
	v_lshl_add_u64 v[18:19], v[18:19], 0, s[90:91]
	s_waitcnt lgkmcnt(0)
	v_add_f32_e32 v16, v16, v17
	global_store_dword v[18:19], v16, off
.LBB0_1403:
	s_or_b64 exec, exec, s[24:25]
	s_waitcnt lgkmcnt(0)
	v_lshlrev_b64 v[16:17], 10, v[114:115]
	v_lshl_add_u64 v[20:21], v[16:17], 0, v[200:201]
	v_lshl_add_u64 v[22:23], v[20:21], 2, s[10:11]
	global_store_dwordx4 v[22:23], v[12:15], off
	global_store_dwordx4 v[22:23], v[8:11], off offset:16
	v_cvt_pk_bf16_f32 v16, v12, v13
	v_mul_f32_e32 v13, v13, v13
	v_fmac_f32_e32 v13, v12, v12
	v_mul_f32_e32 v12, v15, v15
	v_cvt_pk_bf16_f32 v18, v8, v9
	v_fmac_f32_e32 v12, v14, v14
	v_mul_f32_e32 v9, v9, v9
	v_add_f32_e32 v12, v13, v12
	v_fmac_f32_e32 v9, v8, v8
	v_add_f32_e32 v8, v9, v12
	v_mul_f32_e32 v9, v11, v11
	v_fmac_f32_e32 v9, v10, v10
	v_cvt_pk_bf16_f32 v19, v10, v11
	v_add_f32_e32 v8, v9, v8
	v_mul_f32_e32 v9, v5, v5
	v_mul_f32_e32 v10, v7, v7
	v_fmac_f32_e32 v9, v4, v4
	v_fmac_f32_e32 v10, v6, v6
	v_add_f32_e32 v9, v9, v10
	v_mul_f32_e32 v10, v1, v1
	v_fmac_f32_e32 v10, v0, v0
	v_add_f32_e32 v9, v10, v9
	v_mul_f32_e32 v10, v3, v3
	v_fmac_f32_e32 v10, v2, v2
	v_add_f32_e32 v9, v10, v9
	v_add_f32_e32 v8, v8, v9
	ds_bpermute_b32 v9, v217, v8
	v_lshlrev_b64 v[20:21], 1, v[20:21]
	v_cvt_pk_bf16_f32 v17, v14, v15
	v_lshl_add_u64 v[24:25], s[16:17], 0, v[20:21]
	global_store_dwordx4 v[24:25], v[16:19], off
	global_store_dwordx4 v[22:23], v[4:7], off offset:512
	global_store_dwordx4 v[22:23], v[0:3], off offset:528
	v_or_b32_e32 v20, 0x100, v20
	v_cvt_pk_bf16_f32 v4, v4, v5
	v_cvt_pk_bf16_f32 v5, v6, v7
	v_cvt_pk_bf16_f32 v6, v0, v1
	s_waitcnt lgkmcnt(0)
	v_add_f32_e32 v0, v8, v9
	ds_bpermute_b32 v1, v216, v0
	v_cvt_pk_bf16_f32 v7, v2, v3
	v_lshl_add_u64 v[2:3], s[16:17], 0, v[20:21]
	global_store_dwordx4 v[2:3], v[4:7], off
	s_and_saveexec_b64 s[24:25], s[4:5]
	s_cbranch_execz .LBB0_1405
	v_lshlrev_b64 v[2:3], 6, v[114:115]
	v_lshl_add_u64 v[2:3], s[18:19], 0, v[2:3]
	v_lshl_add_u64 v[2:3], s[40:41], 2, v[2:3]
	s_lshl_b32 s90, s71, 2
	v_lshl_add_u64 v[2:3], v[2:3], 0, s[90:91]
	s_waitcnt lgkmcnt(0)
	v_add_f32_e32 v0, v0, v1
	global_store_dword v[2:3], v0, off
